# GEMM K loops (kind 1 and 2): loop-edge scalar work (pointer bumps, exit test, next iteration's selects) moved in front of the iteration's last barrier; exit flag carried in an SGPR
# baseline (speedup 1.0000x reference)
.Lzp2_go:
	s_add_u32 s18, s18, 0x80
	s_addc_u32 s19, s19, 0
	s_add_u32 s35, s20, 0x100
	s_addc_u32 s38, s21, 0
	s_mov_b32 s20, 0
	s_add_i32 s39, s20, 2
	s_add_u32 s40, s18, 0x80
	s_addc_u32 s21, s19, 0
	s_add_i32 s51, s33, 0x100
	s_cmp_eq_u32 s47, s20
	s_cselect_b32 s21, s1, s21
	s_cselect_b32 s20, s0, s40
	v_add_u32_e32 v152, s51, v155
	s_cselect_b32 s41, s17, s38
	s_cselect_b32 s40, s16, s35
	s_add_i32 s52, s29, 0x100
	ds_read_b128 v[130:133], v152
	ds_read_b128 v[144:147], v152 offset:1024
	ds_read_b128 v[148:151], v152 offset:2048
	ds_read_b128 v[192:195], v152 offset:3072
	v_add_u32_e32 v152, s52, v155
	ds_read_b128 v[196:199], v152
	ds_read_b128 v[200:203], v152 offset:1024
	ds_read_b128 v[204:207], v152 offset:2048
	ds_read_b128 v[208:211], v152 offset:3072
	v_lshl_add_u64 v[152:153], s[18:19], 0, v[140:141]
	s_add_i32 m0, s27, 0xc000
	ds_read_b128 v[212:215], v165
	ds_read_b128 v[216:219], v165 offset:1024
	ds_read_b128 v[220:223], v165 offset:2048
	ds_read_b128 v[224:227], v165 offset:3072
	ds_read_b128 v[228:231], v165 offset:4096
	ds_read_b128 v[232:235], v165 offset:5120
	ds_read_b128 v[236:239], v165 offset:6144
	ds_read_b128 v[240:243], v165 offset:7168
	global_load_lds_dwordx4 v[152:153], off
	v_lshl_add_u64 v[152:153], s[18:19], 0, v[142:143]
	s_add_i32 m0, s27, 0xe000
	s_nop 0
	global_load_lds_dwordx4 v[152:153], off
	s_waitcnt vmcnt(8)
	s_waitcnt lgkmcnt(0)
	s_barrier
	s_setprio 1
	s_waitcnt lgkmcnt(0)
	v_mfma_f32_16x16x32_bf16 v[126:129], v[130:133], v[212:215], 0
	v_mfma_f32_16x16x32_bf16 v[122:125], v[148:151], v[212:215], 0
	v_mfma_f32_16x16x32_bf16 v[108:111], v[130:133], v[220:223], 0
	v_mfma_f32_16x16x32_bf16 v[104:107], v[148:151], v[220:223], 0
	v_mfma_f32_16x16x32_bf16 v[92:95], v[130:133], v[228:231], 0
	v_mfma_f32_16x16x32_bf16 v[88:91], v[148:151], v[228:231], 0
	v_mfma_f32_16x16x32_bf16 v[76:79], v[130:133], v[236:239], 0
	v_mfma_f32_16x16x32_bf16 v[72:75], v[148:151], v[236:239], 0
	v_mfma_f32_16x16x32_bf16 v[126:129], v[144:147], v[216:219], v[126:129]
	v_mfma_f32_16x16x32_bf16 v[122:125], v[192:195], v[216:219], v[122:125]
	v_mfma_f32_16x16x32_bf16 v[108:111], v[144:147], v[224:227], v[108:111]
	v_mfma_f32_16x16x32_bf16 v[104:107], v[192:195], v[224:227], v[104:107]
	v_mfma_f32_16x16x32_bf16 v[92:95], v[144:147], v[232:235], v[92:95]
	v_mfma_f32_16x16x32_bf16 v[88:91], v[192:195], v[232:235], v[88:91]
	v_mfma_f32_16x16x32_bf16 v[76:79], v[144:147], v[240:243], v[76:79]
	v_mfma_f32_16x16x32_bf16 v[72:75], v[192:195], v[240:243], v[72:75]
	s_setprio 0
	s_setprio 1
	v_mfma_f32_16x16x32_bf16 v[118:121], v[196:199], v[212:215], 0
	v_mfma_f32_16x16x32_bf16 v[114:117], v[204:207], v[212:215], 0
	v_mfma_f32_16x16x32_bf16 v[100:103], v[196:199], v[220:223], 0
	v_mfma_f32_16x16x32_bf16 v[96:99], v[204:207], v[220:223], 0
	v_mfma_f32_16x16x32_bf16 v[84:87], v[196:199], v[228:231], 0
	v_mfma_f32_16x16x32_bf16 v[80:83], v[204:207], v[228:231], 0
	v_mfma_f32_16x16x32_bf16 v[68:71], v[196:199], v[236:239], 0
	v_mfma_f32_16x16x32_bf16 v[64:67], v[204:207], v[236:239], 0
	v_mfma_f32_16x16x32_bf16 v[118:121], v[200:203], v[216:219], v[118:121]
	v_mfma_f32_16x16x32_bf16 v[114:117], v[208:211], v[216:219], v[114:117]
	v_mfma_f32_16x16x32_bf16 v[100:103], v[200:203], v[224:227], v[100:103]
	v_mfma_f32_16x16x32_bf16 v[96:99], v[208:211], v[224:227], v[96:99]
	v_mfma_f32_16x16x32_bf16 v[84:87], v[200:203], v[232:235], v[84:87]
	v_mfma_f32_16x16x32_bf16 v[80:83], v[208:211], v[232:235], v[80:83]
	v_mfma_f32_16x16x32_bf16 v[68:71], v[200:203], v[240:243], v[68:71]
	v_mfma_f32_16x16x32_bf16 v[64:67], v[208:211], v[240:243], v[64:67]
	s_setprio 0
	s_barrier
	s_add_i32 s51, s51, s26
	v_lshl_add_u64 v[152:153], s[40:41], 0, v[112:113]
	s_mov_b32 m0, s51
	ds_read_b128 v[212:215], v165 offset:16384
	ds_read_b128 v[216:219], v165 offset:17408
	ds_read_b128 v[220:223], v165 offset:18432
	ds_read_b128 v[224:227], v165 offset:19456
	ds_read_b128 v[228:231], v165 offset:20480
	ds_read_b128 v[232:235], v165 offset:21504
	ds_read_b128 v[236:239], v165 offset:22528
	ds_read_b128 v[240:243], v165 offset:23552
	global_load_lds_dwordx4 v[152:153], off
	s_add_i32 m0, s51, 0x2000
	v_lshl_add_u64 v[170:171], s[40:41], 0, v[134:135]
	s_add_u32 s40, s40, s2
	s_addc_u32 s41, s41, 0
	s_add_i32 s51, s52, s26
	global_load_lds_dwordx4 v[170:171], off
	v_lshl_add_u64 v[176:177], s[40:41], 0, v[112:113]
	s_mov_b32 m0, s51
	v_lshl_add_u64 v[178:179], s[40:41], 0, v[134:135]
	global_load_lds_dwordx4 v[176:177], off
	s_add_i32 m0, s51, 0x2000
	v_lshl_add_u64 v[180:181], s[20:21], 0, v[138:139]
	global_load_lds_dwordx4 v[178:179], off
	s_mov_b32 m0, s27
	v_lshl_add_u64 v[244:245], s[20:21], 0, v[136:137]
	global_load_lds_dwordx4 v[180:181], off
	s_mov_b32 m0, s42
	s_nop 0
	global_load_lds_dwordx4 v[244:245], off
	s_waitcnt vmcnt(8)
	s_waitcnt lgkmcnt(0)
	s_barrier
	s_setprio 1
	s_waitcnt lgkmcnt(0)
	v_mfma_f32_16x16x32_bf16 v[60:63], v[130:133], v[212:215], 0
	v_mfma_f32_16x16x32_bf16 v[56:59], v[148:151], v[212:215], 0
	v_mfma_f32_16x16x32_bf16 v[44:47], v[130:133], v[220:223], 0
	v_mfma_f32_16x16x32_bf16 v[40:43], v[148:151], v[220:223], 0
	v_mfma_f32_16x16x32_bf16 v[28:31], v[130:133], v[228:231], 0
	v_mfma_f32_16x16x32_bf16 v[24:27], v[148:151], v[228:231], 0
	v_mfma_f32_16x16x32_bf16 v[12:15], v[130:133], v[236:239], 0
	v_mfma_f32_16x16x32_bf16 v[8:11], v[148:151], v[236:239], 0
	v_mfma_f32_16x16x32_bf16 v[60:63], v[144:147], v[216:219], v[60:63]
	v_mfma_f32_16x16x32_bf16 v[56:59], v[192:195], v[216:219], v[56:59]
	v_mfma_f32_16x16x32_bf16 v[44:47], v[144:147], v[224:227], v[44:47]
	v_mfma_f32_16x16x32_bf16 v[40:43], v[192:195], v[224:227], v[40:43]
	v_mfma_f32_16x16x32_bf16 v[28:31], v[144:147], v[232:235], v[28:31]
	v_mfma_f32_16x16x32_bf16 v[24:27], v[192:195], v[232:235], v[24:27]
	v_mfma_f32_16x16x32_bf16 v[12:15], v[144:147], v[240:243], v[12:15]
	v_mfma_f32_16x16x32_bf16 v[8:11], v[192:195], v[240:243], v[8:11]
	s_setprio 0
	s_setprio 1
	v_mfma_f32_16x16x32_bf16 v[52:55], v[196:199], v[212:215], 0
	v_mfma_f32_16x16x32_bf16 v[48:51], v[204:207], v[212:215], 0
	v_mfma_f32_16x16x32_bf16 v[36:39], v[196:199], v[220:223], 0
	v_mfma_f32_16x16x32_bf16 v[32:35], v[204:207], v[220:223], 0
	v_mfma_f32_16x16x32_bf16 v[20:23], v[196:199], v[228:231], 0
	v_mfma_f32_16x16x32_bf16 v[16:19], v[204:207], v[228:231], 0
	v_mfma_f32_16x16x32_bf16 v[4:7], v[196:199], v[236:239], 0
	v_mfma_f32_16x16x32_bf16 v[0:3], v[204:207], v[236:239], 0
	v_mfma_f32_16x16x32_bf16 v[52:55], v[200:203], v[216:219], v[52:55]
	v_mfma_f32_16x16x32_bf16 v[48:51], v[208:211], v[216:219], v[48:51]
	v_mfma_f32_16x16x32_bf16 v[36:39], v[200:203], v[224:227], v[36:39]
	v_mfma_f32_16x16x32_bf16 v[32:35], v[208:211], v[224:227], v[32:35]
	v_mfma_f32_16x16x32_bf16 v[20:23], v[200:203], v[232:235], v[20:23]
	v_mfma_f32_16x16x32_bf16 v[16:19], v[208:211], v[232:235], v[16:19]
	v_mfma_f32_16x16x32_bf16 v[4:7], v[200:203], v[240:243], v[4:7]
	v_mfma_f32_16x16x32_bf16 v[0:3], v[208:211], v[240:243], v[0:3]
	s_setprio 0
	s_barrier
	s_add_i32 s40, s8, 0x100
	v_add_u32_e32 v191, s40, v155
	s_add_i32 s41, s9, 0x100
	ds_read_b128 v[130:133], v191
	ds_read_b128 v[144:147], v191 offset:1024
	ds_read_b128 v[148:151], v191 offset:2048
	ds_read_b128 v[192:195], v191 offset:3072
	v_add_u32_e32 v191, s41, v155
	ds_read_b128 v[196:199], v191
	ds_read_b128 v[200:203], v191 offset:1024
	ds_read_b128 v[204:207], v191 offset:2048
	ds_read_b128 v[208:211], v191 offset:3072
	s_add_u32 s20, s20, s2
	s_addc_u32 s21, s21, 0
	s_mov_b32 m0, s43
	v_lshl_add_u64 v[246:247], s[20:21], 0, v[138:139]
	ds_read_b128 v[212:215], v165 offset:32768
	ds_read_b128 v[216:219], v165 offset:33792
	ds_read_b128 v[220:223], v165 offset:34816
	ds_read_b128 v[224:227], v165 offset:35840
	ds_read_b128 v[228:231], v165 offset:36864
	ds_read_b128 v[232:235], v165 offset:37888
	ds_read_b128 v[236:239], v165 offset:38912
	ds_read_b128 v[240:243], v165 offset:39936
	global_load_lds_dwordx4 v[246:247], off
	v_lshl_add_u64 v[246:247], s[20:21], 0, v[136:137]
	s_mov_b32 m0, s44
	s_nop 0
	global_load_lds_dwordx4 v[246:247], off
	s_waitcnt vmcnt(8)
	s_waitcnt lgkmcnt(0)
	s_barrier
	s_setprio 1
	s_waitcnt lgkmcnt(0)
	v_mfma_f32_16x16x32_bf16 v[126:129], v[130:133], v[212:215], v[126:129]
	v_mfma_f32_16x16x32_bf16 v[122:125], v[148:151], v[212:215], v[122:125]
	v_mfma_f32_16x16x32_bf16 v[108:111], v[130:133], v[220:223], v[108:111]
	v_mfma_f32_16x16x32_bf16 v[104:107], v[148:151], v[220:223], v[104:107]
	v_mfma_f32_16x16x32_bf16 v[92:95], v[130:133], v[228:231], v[92:95]
	v_mfma_f32_16x16x32_bf16 v[88:91], v[148:151], v[228:231], v[88:91]
	v_mfma_f32_16x16x32_bf16 v[76:79], v[130:133], v[236:239], v[76:79]
	v_mfma_f32_16x16x32_bf16 v[72:75], v[148:151], v[236:239], v[72:75]
	v_mfma_f32_16x16x32_bf16 v[126:129], v[144:147], v[216:219], v[126:129]
	v_mfma_f32_16x16x32_bf16 v[122:125], v[192:195], v[216:219], v[122:125]
	v_mfma_f32_16x16x32_bf16 v[108:111], v[144:147], v[224:227], v[108:111]
	v_mfma_f32_16x16x32_bf16 v[104:107], v[192:195], v[224:227], v[104:107]
	v_mfma_f32_16x16x32_bf16 v[92:95], v[144:147], v[232:235], v[92:95]
	v_mfma_f32_16x16x32_bf16 v[88:91], v[192:195], v[232:235], v[88:91]
	v_mfma_f32_16x16x32_bf16 v[76:79], v[144:147], v[240:243], v[76:79]
	v_mfma_f32_16x16x32_bf16 v[72:75], v[192:195], v[240:243], v[72:75]
	s_setprio 0
	s_setprio 1
	v_mfma_f32_16x16x32_bf16 v[118:121], v[196:199], v[212:215], v[118:121]
	v_mfma_f32_16x16x32_bf16 v[114:117], v[204:207], v[212:215], v[114:117]
	v_mfma_f32_16x16x32_bf16 v[100:103], v[196:199], v[220:223], v[100:103]
	v_mfma_f32_16x16x32_bf16 v[96:99], v[204:207], v[220:223], v[96:99]
	v_mfma_f32_16x16x32_bf16 v[84:87], v[196:199], v[228:231], v[84:87]
	v_mfma_f32_16x16x32_bf16 v[80:83], v[204:207], v[228:231], v[80:83]
	v_mfma_f32_16x16x32_bf16 v[68:71], v[196:199], v[236:239], v[68:71]
	v_mfma_f32_16x16x32_bf16 v[64:67], v[204:207], v[236:239], v[64:67]
	v_mfma_f32_16x16x32_bf16 v[118:121], v[200:203], v[216:219], v[118:121]
	v_mfma_f32_16x16x32_bf16 v[114:117], v[208:211], v[216:219], v[114:117]
	v_mfma_f32_16x16x32_bf16 v[100:103], v[200:203], v[224:227], v[100:103]
	v_mfma_f32_16x16x32_bf16 v[96:99], v[208:211], v[224:227], v[96:99]
	v_mfma_f32_16x16x32_bf16 v[84:87], v[200:203], v[232:235], v[84:87]
	v_mfma_f32_16x16x32_bf16 v[80:83], v[208:211], v[232:235], v[80:83]
	v_mfma_f32_16x16x32_bf16 v[68:71], v[200:203], v[240:243], v[68:71]
	v_mfma_f32_16x16x32_bf16 v[64:67], v[208:211], v[240:243], v[64:67]
	s_setprio 0
	s_barrier
	s_add_i32 s20, s40, s26
	v_lshl_add_u64 v[152:153], v[152:153], 0, s[30:31]
	s_mov_b32 m0, s20
	ds_read_b128 v[212:215], v165 offset:49152
	ds_read_b128 v[216:219], v165 offset:50176
	ds_read_b128 v[220:223], v165 offset:51200
	ds_read_b128 v[224:227], v165 offset:52224
	ds_read_b128 v[228:231], v165 offset:53248
	ds_read_b128 v[232:235], v165 offset:54272
	ds_read_b128 v[236:239], v165 offset:55296
	ds_read_b128 v[240:243], v165 offset:56320
	global_load_lds_dwordx4 v[152:153], off
	v_lshl_add_u64 v[152:153], v[170:171], 0, s[30:31]
	s_add_i32 m0, s20, 0x2000
	s_add_i32 s20, s41, s26
	global_load_lds_dwordx4 v[152:153], off
	v_lshl_add_u64 v[152:153], v[176:177], 0, s[30:31]
	s_mov_b32 m0, s20
	s_nop 0
	global_load_lds_dwordx4 v[152:153], off
	v_lshl_add_u64 v[152:153], v[178:179], 0, s[30:31]
	s_add_i32 m0, s20, 0x2000
	s_nop 0
	global_load_lds_dwordx4 v[152:153], off
	v_lshl_add_u64 v[152:153], v[180:181], 0, s[30:31]
	s_mov_b32 m0, s45
	s_nop 0
	global_load_lds_dwordx4 v[152:153], off
	v_lshl_add_u64 v[152:153], v[244:245], 0, s[30:31]
	s_mov_b32 m0, s46
	s_nop 0
	global_load_lds_dwordx4 v[152:153], off
	s_waitcnt vmcnt(8)
	s_waitcnt lgkmcnt(0)
	s_barrier
	s_setprio 1
	s_waitcnt lgkmcnt(0)
	v_mfma_f32_16x16x32_bf16 v[60:63], v[130:133], v[212:215], v[60:63]
	v_mfma_f32_16x16x32_bf16 v[56:59], v[148:151], v[212:215], v[56:59]
	v_mfma_f32_16x16x32_bf16 v[44:47], v[130:133], v[220:223], v[44:47]
	v_mfma_f32_16x16x32_bf16 v[40:43], v[148:151], v[220:223], v[40:43]
	v_mfma_f32_16x16x32_bf16 v[28:31], v[130:133], v[228:231], v[28:31]
	v_mfma_f32_16x16x32_bf16 v[24:27], v[148:151], v[228:231], v[24:27]
	v_mfma_f32_16x16x32_bf16 v[12:15], v[130:133], v[236:239], v[12:15]
	v_mfma_f32_16x16x32_bf16 v[8:11], v[148:151], v[236:239], v[8:11]
	v_mfma_f32_16x16x32_bf16 v[60:63], v[144:147], v[216:219], v[60:63]
	v_mfma_f32_16x16x32_bf16 v[56:59], v[192:195], v[216:219], v[56:59]
	v_mfma_f32_16x16x32_bf16 v[44:47], v[144:147], v[224:227], v[44:47]
	v_mfma_f32_16x16x32_bf16 v[40:43], v[192:195], v[224:227], v[40:43]
	v_mfma_f32_16x16x32_bf16 v[28:31], v[144:147], v[232:235], v[28:31]
	v_mfma_f32_16x16x32_bf16 v[24:27], v[192:195], v[232:235], v[24:27]
	v_mfma_f32_16x16x32_bf16 v[12:15], v[144:147], v[240:243], v[12:15]
	v_mfma_f32_16x16x32_bf16 v[8:11], v[192:195], v[240:243], v[8:11]
	s_setprio 0
	s_setprio 1
	v_mfma_f32_16x16x32_bf16 v[52:55], v[196:199], v[212:215], v[52:55]
	v_mfma_f32_16x16x32_bf16 v[48:51], v[204:207], v[212:215], v[48:51]
	v_mfma_f32_16x16x32_bf16 v[36:39], v[196:199], v[220:223], v[36:39]
	v_mfma_f32_16x16x32_bf16 v[32:35], v[204:207], v[220:223], v[32:35]
	v_mfma_f32_16x16x32_bf16 v[20:23], v[196:199], v[228:231], v[20:23]
	v_mfma_f32_16x16x32_bf16 v[16:19], v[204:207], v[228:231], v[16:19]
	v_mfma_f32_16x16x32_bf16 v[4:7], v[196:199], v[236:239], v[4:7]
	v_mfma_f32_16x16x32_bf16 v[0:3], v[204:207], v[236:239], v[0:3]
	v_mfma_f32_16x16x32_bf16 v[52:55], v[200:203], v[216:219], v[52:55]
	v_mfma_f32_16x16x32_bf16 v[48:51], v[208:211], v[216:219], v[48:51]
	v_mfma_f32_16x16x32_bf16 v[36:39], v[200:203], v[224:227], v[36:39]
	v_mfma_f32_16x16x32_bf16 v[32:35], v[208:211], v[224:227], v[32:35]
	v_mfma_f32_16x16x32_bf16 v[20:23], v[200:203], v[232:235], v[20:23]
	v_mfma_f32_16x16x32_bf16 v[16:19], v[208:211], v[232:235], v[16:19]
	v_mfma_f32_16x16x32_bf16 v[4:7], v[200:203], v[240:243], v[4:7]
	v_mfma_f32_16x16x32_bf16 v[0:3], v[208:211], v[240:243], v[0:3]
	s_setprio 0
	s_add_u32 s18, s18, 0x100
	s_addc_u32 s19, s19, 0
	s_add_u32 s35, s35, 0x100
	s_addc_u32 s38, s38, 0
	s_cmp_ge_u32 s39, s34
	s_cselect_b32 s101, 1, 0
	s_mov_b32 s20, s39
	s_add_i32 s39, s20, 2
	s_add_u32 s40, s18, 0x80
	s_addc_u32 s21, s19, 0
	s_add_i32 s51, s33, 0x100
	s_cmp_eq_u32 s47, s20
	s_cselect_b32 s21, s1, s21
	s_cselect_b32 s20, s0, s40
	v_add_u32_e32 v152, s51, v155
	s_cselect_b32 s41, s17, s38
	s_cselect_b32 s40, s16, s35
	s_add_i32 s52, s29, 0x100
	s_barrier
	s_cmp_eq_u32 s101, 1
	s_cbranch_scc1 .Lzp2_done
.LBB0_477:
	ds_read_b128 v[130:133], v152
	ds_read_b128 v[144:147], v152 offset:1024
	ds_read_b128 v[148:151], v152 offset:2048
	ds_read_b128 v[192:195], v152 offset:3072
	v_add_u32_e32 v152, s52, v155
	ds_read_b128 v[196:199], v152
	ds_read_b128 v[200:203], v152 offset:1024
	ds_read_b128 v[204:207], v152 offset:2048
	ds_read_b128 v[208:211], v152 offset:3072
	v_lshl_add_u64 v[152:153], s[18:19], 0, v[140:141]
	s_add_i32 m0, s27, 0xc000
	ds_read_b128 v[212:215], v165
	ds_read_b128 v[216:219], v165 offset:1024
	ds_read_b128 v[220:223], v165 offset:2048
	ds_read_b128 v[224:227], v165 offset:3072
	ds_read_b128 v[228:231], v165 offset:4096
	ds_read_b128 v[232:235], v165 offset:5120
	ds_read_b128 v[236:239], v165 offset:6144
	ds_read_b128 v[240:243], v165 offset:7168
	global_load_lds_dwordx4 v[152:153], off
	v_lshl_add_u64 v[152:153], s[18:19], 0, v[142:143]
	s_add_i32 m0, s27, 0xe000
	s_nop 0
	global_load_lds_dwordx4 v[152:153], off
	s_waitcnt vmcnt(8)
	s_waitcnt lgkmcnt(0)
	s_barrier
	s_setprio 1
	s_waitcnt lgkmcnt(0)
	v_mfma_f32_16x16x32_bf16 v[126:129], v[130:133], v[212:215], v[126:129]
	v_mfma_f32_16x16x32_bf16 v[122:125], v[148:151], v[212:215], v[122:125]
	v_mfma_f32_16x16x32_bf16 v[108:111], v[130:133], v[220:223], v[108:111]
	v_mfma_f32_16x16x32_bf16 v[104:107], v[148:151], v[220:223], v[104:107]
	v_mfma_f32_16x16x32_bf16 v[92:95], v[130:133], v[228:231], v[92:95]
	v_mfma_f32_16x16x32_bf16 v[88:91], v[148:151], v[228:231], v[88:91]
	v_mfma_f32_16x16x32_bf16 v[76:79], v[130:133], v[236:239], v[76:79]
	v_mfma_f32_16x16x32_bf16 v[72:75], v[148:151], v[236:239], v[72:75]
	v_mfma_f32_16x16x32_bf16 v[126:129], v[144:147], v[216:219], v[126:129]
	v_mfma_f32_16x16x32_bf16 v[122:125], v[192:195], v[216:219], v[122:125]
	v_mfma_f32_16x16x32_bf16 v[108:111], v[144:147], v[224:227], v[108:111]
	v_mfma_f32_16x16x32_bf16 v[104:107], v[192:195], v[224:227], v[104:107]
	v_mfma_f32_16x16x32_bf16 v[92:95], v[144:147], v[232:235], v[92:95]
	v_mfma_f32_16x16x32_bf16 v[88:91], v[192:195], v[232:235], v[88:91]
	v_mfma_f32_16x16x32_bf16 v[76:79], v[144:147], v[240:243], v[76:79]
	v_mfma_f32_16x16x32_bf16 v[72:75], v[192:195], v[240:243], v[72:75]
	s_setprio 0
	s_setprio 1
	v_mfma_f32_16x16x32_bf16 v[118:121], v[196:199], v[212:215], v[118:121]
	v_mfma_f32_16x16x32_bf16 v[114:117], v[204:207], v[212:215], v[114:117]
	v_mfma_f32_16x16x32_bf16 v[100:103], v[196:199], v[220:223], v[100:103]
	v_mfma_f32_16x16x32_bf16 v[96:99], v[204:207], v[220:223], v[96:99]
	v_mfma_f32_16x16x32_bf16 v[84:87], v[196:199], v[228:231], v[84:87]
	v_mfma_f32_16x16x32_bf16 v[80:83], v[204:207], v[228:231], v[80:83]
	v_mfma_f32_16x16x32_bf16 v[68:71], v[196:199], v[236:239], v[68:71]
	v_mfma_f32_16x16x32_bf16 v[64:67], v[204:207], v[236:239], v[64:67]
	v_mfma_f32_16x16x32_bf16 v[118:121], v[200:203], v[216:219], v[118:121]
	v_mfma_f32_16x16x32_bf16 v[114:117], v[208:211], v[216:219], v[114:117]
	v_mfma_f32_16x16x32_bf16 v[100:103], v[200:203], v[224:227], v[100:103]
	v_mfma_f32_16x16x32_bf16 v[96:99], v[208:211], v[224:227], v[96:99]
	v_mfma_f32_16x16x32_bf16 v[84:87], v[200:203], v[232:235], v[84:87]
	v_mfma_f32_16x16x32_bf16 v[80:83], v[208:211], v[232:235], v[80:83]
	v_mfma_f32_16x16x32_bf16 v[68:71], v[200:203], v[240:243], v[68:71]
	v_mfma_f32_16x16x32_bf16 v[64:67], v[208:211], v[240:243], v[64:67]
	s_setprio 0
	s_barrier
	s_add_i32 s51, s51, s26
	v_lshl_add_u64 v[152:153], s[40:41], 0, v[112:113]
	s_mov_b32 m0, s51
	ds_read_b128 v[212:215], v165 offset:16384
	ds_read_b128 v[216:219], v165 offset:17408
	ds_read_b128 v[220:223], v165 offset:18432
	ds_read_b128 v[224:227], v165 offset:19456
	ds_read_b128 v[228:231], v165 offset:20480
	ds_read_b128 v[232:235], v165 offset:21504
	ds_read_b128 v[236:239], v165 offset:22528
	ds_read_b128 v[240:243], v165 offset:23552
	global_load_lds_dwordx4 v[152:153], off
	s_add_i32 m0, s51, 0x2000
	v_lshl_add_u64 v[170:171], s[40:41], 0, v[134:135]
	s_add_u32 s40, s40, s2
	s_addc_u32 s41, s41, 0
	s_add_i32 s51, s52, s26
	global_load_lds_dwordx4 v[170:171], off
	v_lshl_add_u64 v[176:177], s[40:41], 0, v[112:113]
	s_mov_b32 m0, s51
	v_lshl_add_u64 v[178:179], s[40:41], 0, v[134:135]
	global_load_lds_dwordx4 v[176:177], off
	s_add_i32 m0, s51, 0x2000
	v_lshl_add_u64 v[180:181], s[20:21], 0, v[138:139]
	global_load_lds_dwordx4 v[178:179], off
	s_mov_b32 m0, s27
	v_lshl_add_u64 v[244:245], s[20:21], 0, v[136:137]
	global_load_lds_dwordx4 v[180:181], off
	s_mov_b32 m0, s42
	s_nop 0
	global_load_lds_dwordx4 v[244:245], off
	s_waitcnt vmcnt(8)
	s_waitcnt lgkmcnt(0)
	s_barrier
	s_setprio 1
	s_waitcnt lgkmcnt(0)
	v_mfma_f32_16x16x32_bf16 v[60:63], v[130:133], v[212:215], v[60:63]
	v_mfma_f32_16x16x32_bf16 v[56:59], v[148:151], v[212:215], v[56:59]
	v_mfma_f32_16x16x32_bf16 v[44:47], v[130:133], v[220:223], v[44:47]
	v_mfma_f32_16x16x32_bf16 v[40:43], v[148:151], v[220:223], v[40:43]
	v_mfma_f32_16x16x32_bf16 v[28:31], v[130:133], v[228:231], v[28:31]
	v_mfma_f32_16x16x32_bf16 v[24:27], v[148:151], v[228:231], v[24:27]
	v_mfma_f32_16x16x32_bf16 v[12:15], v[130:133], v[236:239], v[12:15]
	v_mfma_f32_16x16x32_bf16 v[8:11], v[148:151], v[236:239], v[8:11]
	v_mfma_f32_16x16x32_bf16 v[60:63], v[144:147], v[216:219], v[60:63]
	v_mfma_f32_16x16x32_bf16 v[56:59], v[192:195], v[216:219], v[56:59]
	v_mfma_f32_16x16x32_bf16 v[44:47], v[144:147], v[224:227], v[44:47]
	v_mfma_f32_16x16x32_bf16 v[40:43], v[192:195], v[224:227], v[40:43]
	v_mfma_f32_16x16x32_bf16 v[28:31], v[144:147], v[232:235], v[28:31]
	v_mfma_f32_16x16x32_bf16 v[24:27], v[192:195], v[232:235], v[24:27]
	v_mfma_f32_16x16x32_bf16 v[12:15], v[144:147], v[240:243], v[12:15]
	v_mfma_f32_16x16x32_bf16 v[8:11], v[192:195], v[240:243], v[8:11]
	s_setprio 0
	s_setprio 1
	v_mfma_f32_16x16x32_bf16 v[52:55], v[196:199], v[212:215], v[52:55]
	v_mfma_f32_16x16x32_bf16 v[48:51], v[204:207], v[212:215], v[48:51]
	v_mfma_f32_16x16x32_bf16 v[36:39], v[196:199], v[220:223], v[36:39]
	v_mfma_f32_16x16x32_bf16 v[32:35], v[204:207], v[220:223], v[32:35]
	v_mfma_f32_16x16x32_bf16 v[20:23], v[196:199], v[228:231], v[20:23]
	v_mfma_f32_16x16x32_bf16 v[16:19], v[204:207], v[228:231], v[16:19]
	v_mfma_f32_16x16x32_bf16 v[4:7], v[196:199], v[236:239], v[4:7]
	v_mfma_f32_16x16x32_bf16 v[0:3], v[204:207], v[236:239], v[0:3]
	v_mfma_f32_16x16x32_bf16 v[52:55], v[200:203], v[216:219], v[52:55]
	v_mfma_f32_16x16x32_bf16 v[48:51], v[208:211], v[216:219], v[48:51]
	v_mfma_f32_16x16x32_bf16 v[36:39], v[200:203], v[224:227], v[36:39]
	v_mfma_f32_16x16x32_bf16 v[32:35], v[208:211], v[224:227], v[32:35]
	v_mfma_f32_16x16x32_bf16 v[20:23], v[200:203], v[232:235], v[20:23]
	v_mfma_f32_16x16x32_bf16 v[16:19], v[208:211], v[232:235], v[16:19]
	v_mfma_f32_16x16x32_bf16 v[4:7], v[200:203], v[240:243], v[4:7]
	v_mfma_f32_16x16x32_bf16 v[0:3], v[208:211], v[240:243], v[0:3]
	s_setprio 0
	s_barrier
	s_add_i32 s40, s8, 0x100
	v_add_u32_e32 v191, s40, v155
	s_add_i32 s41, s9, 0x100
	ds_read_b128 v[130:133], v191
	ds_read_b128 v[144:147], v191 offset:1024
	ds_read_b128 v[148:151], v191 offset:2048
	ds_read_b128 v[192:195], v191 offset:3072
	v_add_u32_e32 v191, s41, v155
	ds_read_b128 v[196:199], v191
	ds_read_b128 v[200:203], v191 offset:1024
	ds_read_b128 v[204:207], v191 offset:2048
	ds_read_b128 v[208:211], v191 offset:3072
	s_add_u32 s20, s20, s2
	s_addc_u32 s21, s21, 0
	s_mov_b32 m0, s43
	v_lshl_add_u64 v[246:247], s[20:21], 0, v[138:139]
	ds_read_b128 v[212:215], v165 offset:32768
	ds_read_b128 v[216:219], v165 offset:33792
	ds_read_b128 v[220:223], v165 offset:34816
	ds_read_b128 v[224:227], v165 offset:35840
	ds_read_b128 v[228:231], v165 offset:36864
	ds_read_b128 v[232:235], v165 offset:37888
	ds_read_b128 v[236:239], v165 offset:38912
	ds_read_b128 v[240:243], v165 offset:39936
	global_load_lds_dwordx4 v[246:247], off
	v_lshl_add_u64 v[246:247], s[20:21], 0, v[136:137]
	s_mov_b32 m0, s44
	s_nop 0
	global_load_lds_dwordx4 v[246:247], off
	s_waitcnt vmcnt(8)
	s_waitcnt lgkmcnt(0)
	s_barrier
	s_setprio 1
	s_waitcnt lgkmcnt(0)
	v_mfma_f32_16x16x32_bf16 v[126:129], v[130:133], v[212:215], v[126:129]
	v_mfma_f32_16x16x32_bf16 v[122:125], v[148:151], v[212:215], v[122:125]
	v_mfma_f32_16x16x32_bf16 v[108:111], v[130:133], v[220:223], v[108:111]
	v_mfma_f32_16x16x32_bf16 v[104:107], v[148:151], v[220:223], v[104:107]
	v_mfma_f32_16x16x32_bf16 v[92:95], v[130:133], v[228:231], v[92:95]
	v_mfma_f32_16x16x32_bf16 v[88:91], v[148:151], v[228:231], v[88:91]
	v_mfma_f32_16x16x32_bf16 v[76:79], v[130:133], v[236:239], v[76:79]
	v_mfma_f32_16x16x32_bf16 v[72:75], v[148:151], v[236:239], v[72:75]
	v_mfma_f32_16x16x32_bf16 v[126:129], v[144:147], v[216:219], v[126:129]
	v_mfma_f32_16x16x32_bf16 v[122:125], v[192:195], v[216:219], v[122:125]
	v_mfma_f32_16x16x32_bf16 v[108:111], v[144:147], v[224:227], v[108:111]
	v_mfma_f32_16x16x32_bf16 v[104:107], v[192:195], v[224:227], v[104:107]
	v_mfma_f32_16x16x32_bf16 v[92:95], v[144:147], v[232:235], v[92:95]
	v_mfma_f32_16x16x32_bf16 v[88:91], v[192:195], v[232:235], v[88:91]
	v_mfma_f32_16x16x32_bf16 v[76:79], v[144:147], v[240:243], v[76:79]
	v_mfma_f32_16x16x32_bf16 v[72:75], v[192:195], v[240:243], v[72:75]
	s_setprio 0
	s_setprio 1
	v_mfma_f32_16x16x32_bf16 v[118:121], v[196:199], v[212:215], v[118:121]
	v_mfma_f32_16x16x32_bf16 v[114:117], v[204:207], v[212:215], v[114:117]
	v_mfma_f32_16x16x32_bf16 v[100:103], v[196:199], v[220:223], v[100:103]
	v_mfma_f32_16x16x32_bf16 v[96:99], v[204:207], v[220:223], v[96:99]
	v_mfma_f32_16x16x32_bf16 v[84:87], v[196:199], v[228:231], v[84:87]
	v_mfma_f32_16x16x32_bf16 v[80:83], v[204:207], v[228:231], v[80:83]
	v_mfma_f32_16x16x32_bf16 v[68:71], v[196:199], v[236:239], v[68:71]
	v_mfma_f32_16x16x32_bf16 v[64:67], v[204:207], v[236:239], v[64:67]
	v_mfma_f32_16x16x32_bf16 v[118:121], v[200:203], v[216:219], v[118:121]
	v_mfma_f32_16x16x32_bf16 v[114:117], v[208:211], v[216:219], v[114:117]
	v_mfma_f32_16x16x32_bf16 v[100:103], v[200:203], v[224:227], v[100:103]
	v_mfma_f32_16x16x32_bf16 v[96:99], v[208:211], v[224:227], v[96:99]
	v_mfma_f32_16x16x32_bf16 v[84:87], v[200:203], v[232:235], v[84:87]
	v_mfma_f32_16x16x32_bf16 v[80:83], v[208:211], v[232:235], v[80:83]
	v_mfma_f32_16x16x32_bf16 v[68:71], v[200:203], v[240:243], v[68:71]
	v_mfma_f32_16x16x32_bf16 v[64:67], v[208:211], v[240:243], v[64:67]
	s_setprio 0
	s_barrier
	s_add_i32 s20, s40, s26
	v_lshl_add_u64 v[152:153], v[152:153], 0, s[30:31]
	s_mov_b32 m0, s20
	ds_read_b128 v[212:215], v165 offset:49152
	ds_read_b128 v[216:219], v165 offset:50176
	ds_read_b128 v[220:223], v165 offset:51200
	ds_read_b128 v[224:227], v165 offset:52224
	ds_read_b128 v[228:231], v165 offset:53248
	ds_read_b128 v[232:235], v165 offset:54272
	ds_read_b128 v[236:239], v165 offset:55296
	ds_read_b128 v[240:243], v165 offset:56320
	global_load_lds_dwordx4 v[152:153], off
	v_lshl_add_u64 v[152:153], v[170:171], 0, s[30:31]
	s_add_i32 m0, s20, 0x2000
	s_add_i32 s20, s41, s26
	global_load_lds_dwordx4 v[152:153], off
	v_lshl_add_u64 v[152:153], v[176:177], 0, s[30:31]
	s_mov_b32 m0, s20
	s_nop 0
	global_load_lds_dwordx4 v[152:153], off
	v_lshl_add_u64 v[152:153], v[178:179], 0, s[30:31]
	s_add_i32 m0, s20, 0x2000
	s_nop 0
	global_load_lds_dwordx4 v[152:153], off
	v_lshl_add_u64 v[152:153], v[180:181], 0, s[30:31]
	s_mov_b32 m0, s45
	s_nop 0
	global_load_lds_dwordx4 v[152:153], off
	v_lshl_add_u64 v[152:153], v[244:245], 0, s[30:31]
	s_mov_b32 m0, s46
	s_nop 0
	global_load_lds_dwordx4 v[152:153], off
	s_waitcnt vmcnt(8)
	s_waitcnt lgkmcnt(0)
	s_barrier
	s_setprio 1
	s_waitcnt lgkmcnt(0)
	v_mfma_f32_16x16x32_bf16 v[60:63], v[130:133], v[212:215], v[60:63]
	v_mfma_f32_16x16x32_bf16 v[56:59], v[148:151], v[212:215], v[56:59]
	v_mfma_f32_16x16x32_bf16 v[44:47], v[130:133], v[220:223], v[44:47]
	v_mfma_f32_16x16x32_bf16 v[40:43], v[148:151], v[220:223], v[40:43]
	v_mfma_f32_16x16x32_bf16 v[28:31], v[130:133], v[228:231], v[28:31]
	v_mfma_f32_16x16x32_bf16 v[24:27], v[148:151], v[228:231], v[24:27]
	v_mfma_f32_16x16x32_bf16 v[12:15], v[130:133], v[236:239], v[12:15]
	v_mfma_f32_16x16x32_bf16 v[8:11], v[148:151], v[236:239], v[8:11]
	v_mfma_f32_16x16x32_bf16 v[60:63], v[144:147], v[216:219], v[60:63]
	v_mfma_f32_16x16x32_bf16 v[56:59], v[192:195], v[216:219], v[56:59]
	v_mfma_f32_16x16x32_bf16 v[44:47], v[144:147], v[224:227], v[44:47]
	v_mfma_f32_16x16x32_bf16 v[40:43], v[192:195], v[224:227], v[40:43]
	v_mfma_f32_16x16x32_bf16 v[28:31], v[144:147], v[232:235], v[28:31]
	v_mfma_f32_16x16x32_bf16 v[24:27], v[192:195], v[232:235], v[24:27]
	v_mfma_f32_16x16x32_bf16 v[12:15], v[144:147], v[240:243], v[12:15]
	v_mfma_f32_16x16x32_bf16 v[8:11], v[192:195], v[240:243], v[8:11]
	s_setprio 0
	s_setprio 1
	v_mfma_f32_16x16x32_bf16 v[52:55], v[196:199], v[212:215], v[52:55]
	v_mfma_f32_16x16x32_bf16 v[48:51], v[204:207], v[212:215], v[48:51]
	v_mfma_f32_16x16x32_bf16 v[36:39], v[196:199], v[220:223], v[36:39]
	v_mfma_f32_16x16x32_bf16 v[32:35], v[204:207], v[220:223], v[32:35]
	v_mfma_f32_16x16x32_bf16 v[20:23], v[196:199], v[228:231], v[20:23]
	v_mfma_f32_16x16x32_bf16 v[16:19], v[204:207], v[228:231], v[16:19]
	v_mfma_f32_16x16x32_bf16 v[4:7], v[196:199], v[236:239], v[4:7]
	v_mfma_f32_16x16x32_bf16 v[0:3], v[204:207], v[236:239], v[0:3]
	v_mfma_f32_16x16x32_bf16 v[52:55], v[200:203], v[216:219], v[52:55]
	v_mfma_f32_16x16x32_bf16 v[48:51], v[208:211], v[216:219], v[48:51]
	v_mfma_f32_16x16x32_bf16 v[36:39], v[200:203], v[224:227], v[36:39]
	v_mfma_f32_16x16x32_bf16 v[32:35], v[208:211], v[224:227], v[32:35]
	v_mfma_f32_16x16x32_bf16 v[20:23], v[200:203], v[232:235], v[20:23]
	v_mfma_f32_16x16x32_bf16 v[16:19], v[208:211], v[232:235], v[16:19]
	v_mfma_f32_16x16x32_bf16 v[4:7], v[200:203], v[240:243], v[4:7]
	v_mfma_f32_16x16x32_bf16 v[0:3], v[208:211], v[240:243], v[0:3]
	s_setprio 0
	s_add_u32 s18, s18, 0x100
	s_addc_u32 s19, s19, 0
	s_add_u32 s35, s35, 0x100
	s_addc_u32 s38, s38, 0
	s_cmp_ge_u32 s39, s34
	s_cselect_b32 s101, 1, 0
	s_mov_b32 s20, s39
	s_add_i32 s39, s20, 2
	s_add_u32 s40, s18, 0x80
	s_addc_u32 s21, s19, 0
	s_add_i32 s51, s33, 0x100
	s_cmp_eq_u32 s47, s20
	s_cselect_b32 s21, s1, s21
	s_cselect_b32 s20, s0, s40
	v_add_u32_e32 v152, s51, v155
	s_cselect_b32 s41, s17, s38
	s_cselect_b32 s40, s16, s35
	s_add_i32 s52, s29, 0x100
	s_barrier
	s_cmp_eq_u32 s101, 0
	s_cbranch_scc1 .LBB0_477

.LBB0_673:
	v_readlane_b32 s38, v255, 16
	v_readlane_b32 s39, v255, 17
	s_andn2_b64 vcc, exec, s[38:39]
	s_cbranch_vccnz .LBB0_713
	s_add_u32 s20, s20, 0x80
	s_addc_u32 s21, s21, 0
	s_add_u32 s38, s22, 0x100
	s_addc_u32 s39, s23, 0
	s_mov_b32 s22, 0
	s_add_i32 s54, s22, 2
	s_add_u32 s55, s20, 0x80
	s_addc_u32 s23, s21, 0
	s_add_i32 s58, s33, 0x100
	s_cmp_eq_u32 s44, s22
	s_cselect_b32 s23, s1, s23
	s_cselect_b32 s22, s0, s55
	v_add_u32_e32 v112, s58, v147
	s_cselect_b32 s57, s19, s39
	s_cselect_b32 s56, s18, s38
	s_add_i32 s55, s29, 0x100
	ds_read_b128 v[150:153], v112
	ds_read_b128 v[190:193], v112 offset:1024
	ds_read_b128 v[194:197], v112 offset:2048
	ds_read_b128 v[198:201], v112 offset:3072
	v_add_u32_e32 v112, s55, v147
	ds_read_b128 v[202:205], v112
	ds_read_b128 v[206:209], v112 offset:1024
	ds_read_b128 v[210:213], v112 offset:2048
	ds_read_b128 v[214:217], v112 offset:3072
	v_lshl_add_u64 v[114:115], s[20:21], 0, v[140:141]
	s_add_i32 m0, s27, 0xc000
	ds_read_b128 v[218:221], v149
	ds_read_b128 v[222:225], v149 offset:1024
	ds_read_b128 v[226:229], v149 offset:2048
	ds_read_b128 v[230:233], v149 offset:3072
	ds_read_b128 v[234:237], v149 offset:4096
	ds_read_b128 v[238:241], v149 offset:5120
	ds_read_b128 v[242:245], v149 offset:6144
	ds_read_b128 v[246:249], v149 offset:7168
	global_load_lds_dwordx4 v[114:115], off
	v_lshl_add_u64 v[114:115], s[20:21], 0, v[142:143]
	s_add_i32 m0, s27, 0xe000
	s_nop 0
	global_load_lds_dwordx4 v[114:115], off
	s_waitcnt vmcnt(8)
	s_waitcnt lgkmcnt(0)
	s_barrier
	s_setprio 1
	s_waitcnt lgkmcnt(0)
	v_mfma_f32_16x16x32_bf16 v[128:131], v[150:153], v[218:221], 0
	v_mfma_f32_16x16x32_bf16 v[124:127], v[194:197], v[218:221], 0
	v_mfma_f32_16x16x32_bf16 v[108:111], v[150:153], v[226:229], 0
	v_mfma_f32_16x16x32_bf16 v[104:107], v[194:197], v[226:229], 0
	v_mfma_f32_16x16x32_bf16 v[92:95], v[150:153], v[234:237], 0
	v_mfma_f32_16x16x32_bf16 v[88:91], v[194:197], v[234:237], 0
	v_mfma_f32_16x16x32_bf16 v[76:79], v[150:153], v[242:245], 0
	v_mfma_f32_16x16x32_bf16 v[72:75], v[194:197], v[242:245], 0
	v_mfma_f32_16x16x32_bf16 v[128:131], v[190:193], v[222:225], v[128:131]
	v_mfma_f32_16x16x32_bf16 v[124:127], v[198:201], v[222:225], v[124:127]
	v_mfma_f32_16x16x32_bf16 v[108:111], v[190:193], v[230:233], v[108:111]
	v_mfma_f32_16x16x32_bf16 v[104:107], v[198:201], v[230:233], v[104:107]
	v_mfma_f32_16x16x32_bf16 v[92:95], v[190:193], v[238:241], v[92:95]
	v_mfma_f32_16x16x32_bf16 v[88:91], v[198:201], v[238:241], v[88:91]
	v_mfma_f32_16x16x32_bf16 v[76:79], v[190:193], v[246:249], v[76:79]
	v_mfma_f32_16x16x32_bf16 v[72:75], v[198:201], v[246:249], v[72:75]
	s_setprio 0
	s_setprio 1
	v_mfma_f32_16x16x32_bf16 v[120:123], v[202:205], v[218:221], 0
	v_mfma_f32_16x16x32_bf16 v[114:117], v[210:213], v[218:221], 0
	v_mfma_f32_16x16x32_bf16 v[100:103], v[202:205], v[226:229], 0
	v_mfma_f32_16x16x32_bf16 v[96:99], v[210:213], v[226:229], 0
	v_mfma_f32_16x16x32_bf16 v[84:87], v[202:205], v[234:237], 0
	v_mfma_f32_16x16x32_bf16 v[80:83], v[210:213], v[234:237], 0
	v_mfma_f32_16x16x32_bf16 v[68:71], v[202:205], v[242:245], 0
	v_mfma_f32_16x16x32_bf16 v[64:67], v[210:213], v[242:245], 0
	v_mfma_f32_16x16x32_bf16 v[120:123], v[206:209], v[222:225], v[120:123]
	v_mfma_f32_16x16x32_bf16 v[114:117], v[214:217], v[222:225], v[114:117]
	v_mfma_f32_16x16x32_bf16 v[100:103], v[206:209], v[230:233], v[100:103]
	v_mfma_f32_16x16x32_bf16 v[96:99], v[214:217], v[230:233], v[96:99]
	v_mfma_f32_16x16x32_bf16 v[84:87], v[206:209], v[238:241], v[84:87]
	v_mfma_f32_16x16x32_bf16 v[80:83], v[214:217], v[238:241], v[80:83]
	v_mfma_f32_16x16x32_bf16 v[68:71], v[206:209], v[246:249], v[68:71]
	v_mfma_f32_16x16x32_bf16 v[64:67], v[214:217], v[246:249], v[64:67]
	s_setprio 0
	s_barrier
	s_add_i32 s58, s58, s26
	v_lshl_add_u64 v[144:145], s[56:57], 0, v[134:135]
	s_mov_b32 m0, s58
	ds_read_b128 v[218:221], v149 offset:16384
	ds_read_b128 v[222:225], v149 offset:17408
	ds_read_b128 v[226:229], v149 offset:18432
	ds_read_b128 v[230:233], v149 offset:19456
	ds_read_b128 v[234:237], v149 offset:20480
	ds_read_b128 v[238:241], v149 offset:21504
	ds_read_b128 v[242:245], v149 offset:22528
	ds_read_b128 v[246:249], v149 offset:23552
	global_load_lds_dwordx4 v[144:145], off
	s_add_i32 m0, s58, 0x2000
	v_lshl_add_u64 v[154:155], s[56:57], 0, v[138:139]
	s_add_u32 s56, s56, s100
	s_addc_u32 s57, s57, 0
	s_add_i32 s55, s55, s26
	global_load_lds_dwordx4 v[154:155], off
	v_lshl_add_u64 v[170:171], s[56:57], 0, v[134:135]
	s_mov_b32 m0, s55
	v_lshl_add_u64 v[176:177], s[56:57], 0, v[138:139]
	global_load_lds_dwordx4 v[170:171], off
	s_add_i32 m0, s55, 0x2000
	v_lshl_add_u64 v[178:179], s[22:23], 0, v[132:133]
	global_load_lds_dwordx4 v[176:177], off
	s_mov_b32 m0, s27
	v_lshl_add_u64 v[180:181], s[22:23], 0, v[136:137]
	global_load_lds_dwordx4 v[178:179], off
	s_mov_b32 m0, s35
	s_nop 0
	global_load_lds_dwordx4 v[180:181], off
	s_waitcnt vmcnt(8)
	s_waitcnt lgkmcnt(0)
	s_barrier
	s_setprio 1
	s_waitcnt lgkmcnt(0)
	v_mfma_f32_16x16x32_bf16 v[60:63], v[150:153], v[218:221], 0
	v_mfma_f32_16x16x32_bf16 v[56:59], v[194:197], v[218:221], 0
	v_mfma_f32_16x16x32_bf16 v[44:47], v[150:153], v[226:229], 0
	v_mfma_f32_16x16x32_bf16 v[40:43], v[194:197], v[226:229], 0
	v_mfma_f32_16x16x32_bf16 v[28:31], v[150:153], v[234:237], 0
	v_mfma_f32_16x16x32_bf16 v[24:27], v[194:197], v[234:237], 0
	v_mfma_f32_16x16x32_bf16 v[12:15], v[150:153], v[242:245], 0
	v_mfma_f32_16x16x32_bf16 v[8:11], v[194:197], v[242:245], 0
	v_mfma_f32_16x16x32_bf16 v[60:63], v[190:193], v[222:225], v[60:63]
	v_mfma_f32_16x16x32_bf16 v[56:59], v[198:201], v[222:225], v[56:59]
	v_mfma_f32_16x16x32_bf16 v[44:47], v[190:193], v[230:233], v[44:47]
	v_mfma_f32_16x16x32_bf16 v[40:43], v[198:201], v[230:233], v[40:43]
	v_mfma_f32_16x16x32_bf16 v[28:31], v[190:193], v[238:241], v[28:31]
	v_mfma_f32_16x16x32_bf16 v[24:27], v[198:201], v[238:241], v[24:27]
	v_mfma_f32_16x16x32_bf16 v[12:15], v[190:193], v[246:249], v[12:15]
	v_mfma_f32_16x16x32_bf16 v[8:11], v[198:201], v[246:249], v[8:11]
	s_setprio 0
	s_setprio 1
	v_mfma_f32_16x16x32_bf16 v[52:55], v[202:205], v[218:221], 0
	v_mfma_f32_16x16x32_bf16 v[48:51], v[210:213], v[218:221], 0
	v_mfma_f32_16x16x32_bf16 v[36:39], v[202:205], v[226:229], 0
	v_mfma_f32_16x16x32_bf16 v[32:35], v[210:213], v[226:229], 0
	v_mfma_f32_16x16x32_bf16 v[20:23], v[202:205], v[234:237], 0
	v_mfma_f32_16x16x32_bf16 v[16:19], v[210:213], v[234:237], 0
	v_mfma_f32_16x16x32_bf16 v[4:7], v[202:205], v[242:245], 0
	v_mfma_f32_16x16x32_bf16 v[0:3], v[210:213], v[242:245], 0
	v_mfma_f32_16x16x32_bf16 v[52:55], v[206:209], v[222:225], v[52:55]
	v_mfma_f32_16x16x32_bf16 v[48:51], v[214:217], v[222:225], v[48:51]
	v_mfma_f32_16x16x32_bf16 v[36:39], v[206:209], v[230:233], v[36:39]
	v_mfma_f32_16x16x32_bf16 v[32:35], v[214:217], v[230:233], v[32:35]
	v_mfma_f32_16x16x32_bf16 v[20:23], v[206:209], v[238:241], v[20:23]
	v_mfma_f32_16x16x32_bf16 v[16:19], v[214:217], v[238:241], v[16:19]
	v_mfma_f32_16x16x32_bf16 v[4:7], v[206:209], v[246:249], v[4:7]
	v_mfma_f32_16x16x32_bf16 v[0:3], v[214:217], v[246:249], v[0:3]
	s_setprio 0
	s_barrier
	s_add_i32 s55, s8, 0x100
	v_add_u32_e32 v112, s55, v147
	s_add_i32 s56, s9, 0x100
	ds_read_b128 v[150:153], v112
	ds_read_b128 v[190:193], v112 offset:1024
	ds_read_b128 v[194:197], v112 offset:2048
	ds_read_b128 v[198:201], v112 offset:3072
	v_add_u32_e32 v112, s56, v147
	ds_read_b128 v[202:205], v112
	ds_read_b128 v[206:209], v112 offset:1024
	ds_read_b128 v[210:213], v112 offset:2048
	ds_read_b128 v[214:217], v112 offset:3072
	s_add_u32 s22, s22, s10
	s_addc_u32 s23, s23, 0
	s_mov_b32 m0, s40
	v_lshl_add_u64 v[118:119], s[22:23], 0, v[132:133]
	ds_read_b128 v[218:221], v149 offset:32768
	ds_read_b128 v[222:225], v149 offset:33792
	ds_read_b128 v[226:229], v149 offset:34816
	ds_read_b128 v[230:233], v149 offset:35840
	ds_read_b128 v[234:237], v149 offset:36864
	ds_read_b128 v[238:241], v149 offset:37888
	ds_read_b128 v[242:245], v149 offset:38912
	ds_read_b128 v[246:249], v149 offset:39936
	global_load_lds_dwordx4 v[118:119], off
	v_lshl_add_u64 v[118:119], s[22:23], 0, v[136:137]
	s_mov_b32 m0, s41
	s_nop 0
	global_load_lds_dwordx4 v[118:119], off
	s_waitcnt vmcnt(8)
	s_waitcnt lgkmcnt(0)
	s_barrier
	s_setprio 1
	s_waitcnt lgkmcnt(0)
	v_mfma_f32_16x16x32_bf16 v[128:131], v[150:153], v[218:221], v[128:131]
	v_mfma_f32_16x16x32_bf16 v[124:127], v[194:197], v[218:221], v[124:127]
	v_mfma_f32_16x16x32_bf16 v[108:111], v[150:153], v[226:229], v[108:111]
	v_mfma_f32_16x16x32_bf16 v[104:107], v[194:197], v[226:229], v[104:107]
	v_mfma_f32_16x16x32_bf16 v[92:95], v[150:153], v[234:237], v[92:95]
	v_mfma_f32_16x16x32_bf16 v[88:91], v[194:197], v[234:237], v[88:91]
	v_mfma_f32_16x16x32_bf16 v[76:79], v[150:153], v[242:245], v[76:79]
	v_mfma_f32_16x16x32_bf16 v[72:75], v[194:197], v[242:245], v[72:75]
	v_mfma_f32_16x16x32_bf16 v[128:131], v[190:193], v[222:225], v[128:131]
	v_mfma_f32_16x16x32_bf16 v[124:127], v[198:201], v[222:225], v[124:127]
	v_mfma_f32_16x16x32_bf16 v[108:111], v[190:193], v[230:233], v[108:111]
	v_mfma_f32_16x16x32_bf16 v[104:107], v[198:201], v[230:233], v[104:107]
	v_mfma_f32_16x16x32_bf16 v[92:95], v[190:193], v[238:241], v[92:95]
	v_mfma_f32_16x16x32_bf16 v[88:91], v[198:201], v[238:241], v[88:91]
	v_mfma_f32_16x16x32_bf16 v[76:79], v[190:193], v[246:249], v[76:79]
	v_mfma_f32_16x16x32_bf16 v[72:75], v[198:201], v[246:249], v[72:75]
	s_setprio 0
	s_setprio 1
	v_mfma_f32_16x16x32_bf16 v[118:121], v[202:205], v[218:221], v[120:123]
	v_mfma_f32_16x16x32_bf16 v[114:117], v[210:213], v[218:221], v[114:117]
	v_mfma_f32_16x16x32_bf16 v[100:103], v[202:205], v[226:229], v[100:103]
	v_mfma_f32_16x16x32_bf16 v[96:99], v[210:213], v[226:229], v[96:99]
	v_mfma_f32_16x16x32_bf16 v[84:87], v[202:205], v[234:237], v[84:87]
	v_mfma_f32_16x16x32_bf16 v[80:83], v[210:213], v[234:237], v[80:83]
	v_mfma_f32_16x16x32_bf16 v[68:71], v[202:205], v[242:245], v[68:71]
	v_mfma_f32_16x16x32_bf16 v[64:67], v[210:213], v[242:245], v[64:67]
	v_mfma_f32_16x16x32_bf16 v[120:123], v[206:209], v[222:225], v[118:121]
	v_mfma_f32_16x16x32_bf16 v[116:119], v[214:217], v[222:225], v[114:117]
	v_mfma_f32_16x16x32_bf16 v[100:103], v[206:209], v[230:233], v[100:103]
	v_mfma_f32_16x16x32_bf16 v[96:99], v[214:217], v[230:233], v[96:99]
	v_mfma_f32_16x16x32_bf16 v[84:87], v[206:209], v[238:241], v[84:87]
	v_mfma_f32_16x16x32_bf16 v[80:83], v[214:217], v[238:241], v[80:83]
	v_mfma_f32_16x16x32_bf16 v[68:71], v[206:209], v[246:249], v[68:71]
	v_mfma_f32_16x16x32_bf16 v[64:67], v[214:217], v[246:249], v[64:67]
	s_setprio 0
	s_barrier
	s_add_i32 s22, s55, s26
	v_lshl_add_u64 v[114:115], v[144:145], 0, s[30:31]
	s_mov_b32 m0, s22
	ds_read_b128 v[218:221], v149 offset:49152
	ds_read_b128 v[222:225], v149 offset:50176
	ds_read_b128 v[226:229], v149 offset:51200
	ds_read_b128 v[230:233], v149 offset:52224
	ds_read_b128 v[234:237], v149 offset:53248
	ds_read_b128 v[238:241], v149 offset:54272
	ds_read_b128 v[242:245], v149 offset:55296
	ds_read_b128 v[246:249], v149 offset:56320
	global_load_lds_dwordx4 v[114:115], off
	v_lshl_add_u64 v[114:115], v[154:155], 0, s[30:31]
	s_add_i32 m0, s22, 0x2000
	s_add_i32 s22, s56, s26
	global_load_lds_dwordx4 v[114:115], off
	v_lshl_add_u64 v[114:115], v[170:171], 0, s[30:31]
	s_mov_b32 m0, s22
	s_nop 0
	global_load_lds_dwordx4 v[114:115], off
	v_lshl_add_u64 v[114:115], v[176:177], 0, s[30:31]
	s_add_i32 m0, s22, 0x2000
	s_nop 0
	global_load_lds_dwordx4 v[114:115], off
	v_lshl_add_u64 v[114:115], v[178:179], 0, s[30:31]
	s_mov_b32 m0, s42
	s_nop 0
	global_load_lds_dwordx4 v[114:115], off
	v_lshl_add_u64 v[114:115], v[180:181], 0, s[30:31]
	s_mov_b32 m0, s43
	s_nop 0
	global_load_lds_dwordx4 v[114:115], off
	s_waitcnt vmcnt(8)
	s_waitcnt lgkmcnt(0)
	s_barrier
	s_setprio 1
	s_waitcnt lgkmcnt(0)
	v_mfma_f32_16x16x32_bf16 v[60:63], v[150:153], v[218:221], v[60:63]
	v_mfma_f32_16x16x32_bf16 v[56:59], v[194:197], v[218:221], v[56:59]
	v_mfma_f32_16x16x32_bf16 v[44:47], v[150:153], v[226:229], v[44:47]
	v_mfma_f32_16x16x32_bf16 v[40:43], v[194:197], v[226:229], v[40:43]
	v_mfma_f32_16x16x32_bf16 v[28:31], v[150:153], v[234:237], v[28:31]
	v_mfma_f32_16x16x32_bf16 v[24:27], v[194:197], v[234:237], v[24:27]
	v_mfma_f32_16x16x32_bf16 v[12:15], v[150:153], v[242:245], v[12:15]
	v_mfma_f32_16x16x32_bf16 v[8:11], v[194:197], v[242:245], v[8:11]
	v_mfma_f32_16x16x32_bf16 v[60:63], v[190:193], v[222:225], v[60:63]
	v_mfma_f32_16x16x32_bf16 v[56:59], v[198:201], v[222:225], v[56:59]
	v_mfma_f32_16x16x32_bf16 v[44:47], v[190:193], v[230:233], v[44:47]
	v_mfma_f32_16x16x32_bf16 v[40:43], v[198:201], v[230:233], v[40:43]
	v_mfma_f32_16x16x32_bf16 v[28:31], v[190:193], v[238:241], v[28:31]
	v_mfma_f32_16x16x32_bf16 v[24:27], v[198:201], v[238:241], v[24:27]
	v_mfma_f32_16x16x32_bf16 v[12:15], v[190:193], v[246:249], v[12:15]
	v_mfma_f32_16x16x32_bf16 v[8:11], v[198:201], v[246:249], v[8:11]
	s_setprio 0
	s_setprio 1
	v_mfma_f32_16x16x32_bf16 v[52:55], v[202:205], v[218:221], v[52:55]
	v_mfma_f32_16x16x32_bf16 v[48:51], v[210:213], v[218:221], v[48:51]
	v_mfma_f32_16x16x32_bf16 v[36:39], v[202:205], v[226:229], v[36:39]
	v_mfma_f32_16x16x32_bf16 v[32:35], v[210:213], v[226:229], v[32:35]
	v_mfma_f32_16x16x32_bf16 v[20:23], v[202:205], v[234:237], v[20:23]
	v_mfma_f32_16x16x32_bf16 v[16:19], v[210:213], v[234:237], v[16:19]
	v_mfma_f32_16x16x32_bf16 v[4:7], v[202:205], v[242:245], v[4:7]
	v_mfma_f32_16x16x32_bf16 v[0:3], v[210:213], v[242:245], v[0:3]
	v_mfma_f32_16x16x32_bf16 v[52:55], v[206:209], v[222:225], v[52:55]
	v_mfma_f32_16x16x32_bf16 v[48:51], v[214:217], v[222:225], v[48:51]
	v_mfma_f32_16x16x32_bf16 v[36:39], v[206:209], v[230:233], v[36:39]
	v_mfma_f32_16x16x32_bf16 v[32:35], v[214:217], v[230:233], v[32:35]
	v_mfma_f32_16x16x32_bf16 v[20:23], v[206:209], v[238:241], v[20:23]
	v_mfma_f32_16x16x32_bf16 v[16:19], v[214:217], v[238:241], v[16:19]
	v_mfma_f32_16x16x32_bf16 v[4:7], v[206:209], v[246:249], v[4:7]
	v_mfma_f32_16x16x32_bf16 v[0:3], v[214:217], v[246:249], v[0:3]
	s_setprio 0
	s_add_u32 s20, s20, 0x100
	s_addc_u32 s21, s21, 0
	s_add_u32 s38, s38, 0x100
	s_addc_u32 s39, s39, 0
	s_cmp_ge_u32 s54, s34
	s_cselect_b32 s101, 1, 0
	s_mov_b32 s22, s54
	s_add_i32 s54, s22, 2
	s_add_u32 s55, s20, 0x80
	s_addc_u32 s23, s21, 0
	s_add_i32 s58, s33, 0x100
	s_cmp_eq_u32 s44, s22
	s_cselect_b32 s23, s1, s23
	s_cselect_b32 s22, s0, s55
	v_add_u32_e32 v112, s58, v147
	s_cselect_b32 s57, s19, s39
	s_cselect_b32 s56, s18, s38
	s_add_i32 s55, s29, 0x100
	s_barrier
	s_cmp_eq_u32 s101, 1
	s_cbranch_scc1 .Lzp1_done
.LBB0_675:
	ds_read_b128 v[150:153], v112
	ds_read_b128 v[190:193], v112 offset:1024
	ds_read_b128 v[194:197], v112 offset:2048
	ds_read_b128 v[198:201], v112 offset:3072
	v_add_u32_e32 v112, s55, v147
	ds_read_b128 v[202:205], v112
	ds_read_b128 v[206:209], v112 offset:1024
	ds_read_b128 v[210:213], v112 offset:2048
	ds_read_b128 v[214:217], v112 offset:3072
	v_lshl_add_u64 v[114:115], s[20:21], 0, v[140:141]
	s_add_i32 m0, s27, 0xc000
	ds_read_b128 v[218:221], v149
	ds_read_b128 v[222:225], v149 offset:1024
	ds_read_b128 v[226:229], v149 offset:2048
	ds_read_b128 v[230:233], v149 offset:3072
	ds_read_b128 v[234:237], v149 offset:4096
	ds_read_b128 v[238:241], v149 offset:5120
	ds_read_b128 v[242:245], v149 offset:6144
	ds_read_b128 v[246:249], v149 offset:7168
	global_load_lds_dwordx4 v[114:115], off
	v_lshl_add_u64 v[114:115], s[20:21], 0, v[142:143]
	s_add_i32 m0, s27, 0xe000
	s_nop 0
	global_load_lds_dwordx4 v[114:115], off
	s_waitcnt vmcnt(8)
	s_waitcnt lgkmcnt(0)
	s_barrier
	s_setprio 1
	s_waitcnt lgkmcnt(0)
	v_mfma_f32_16x16x32_bf16 v[128:131], v[150:153], v[218:221], v[128:131]
	v_mfma_f32_16x16x32_bf16 v[124:127], v[194:197], v[218:221], v[124:127]
	v_mfma_f32_16x16x32_bf16 v[108:111], v[150:153], v[226:229], v[108:111]
	v_mfma_f32_16x16x32_bf16 v[104:107], v[194:197], v[226:229], v[104:107]
	v_mfma_f32_16x16x32_bf16 v[92:95], v[150:153], v[234:237], v[92:95]
	v_mfma_f32_16x16x32_bf16 v[88:91], v[194:197], v[234:237], v[88:91]
	v_mfma_f32_16x16x32_bf16 v[76:79], v[150:153], v[242:245], v[76:79]
	v_mfma_f32_16x16x32_bf16 v[72:75], v[194:197], v[242:245], v[72:75]
	v_mfma_f32_16x16x32_bf16 v[128:131], v[190:193], v[222:225], v[128:131]
	v_mfma_f32_16x16x32_bf16 v[124:127], v[198:201], v[222:225], v[124:127]
	v_mfma_f32_16x16x32_bf16 v[108:111], v[190:193], v[230:233], v[108:111]
	v_mfma_f32_16x16x32_bf16 v[104:107], v[198:201], v[230:233], v[104:107]
	v_mfma_f32_16x16x32_bf16 v[92:95], v[190:193], v[238:241], v[92:95]
	v_mfma_f32_16x16x32_bf16 v[88:91], v[198:201], v[238:241], v[88:91]
	v_mfma_f32_16x16x32_bf16 v[76:79], v[190:193], v[246:249], v[76:79]
	v_mfma_f32_16x16x32_bf16 v[72:75], v[198:201], v[246:249], v[72:75]
	s_setprio 0
	s_setprio 1
	v_mfma_f32_16x16x32_bf16 v[120:123], v[202:205], v[218:221], v[120:123]
	v_mfma_f32_16x16x32_bf16 v[114:117], v[210:213], v[218:221], v[116:119]
	v_mfma_f32_16x16x32_bf16 v[100:103], v[202:205], v[226:229], v[100:103]
	v_mfma_f32_16x16x32_bf16 v[96:99], v[210:213], v[226:229], v[96:99]
	v_mfma_f32_16x16x32_bf16 v[84:87], v[202:205], v[234:237], v[84:87]
	v_mfma_f32_16x16x32_bf16 v[80:83], v[210:213], v[234:237], v[80:83]
	v_mfma_f32_16x16x32_bf16 v[68:71], v[202:205], v[242:245], v[68:71]
	v_mfma_f32_16x16x32_bf16 v[64:67], v[210:213], v[242:245], v[64:67]
	v_mfma_f32_16x16x32_bf16 v[120:123], v[206:209], v[222:225], v[120:123]
	v_mfma_f32_16x16x32_bf16 v[114:117], v[214:217], v[222:225], v[114:117]
	v_mfma_f32_16x16x32_bf16 v[100:103], v[206:209], v[230:233], v[100:103]
	v_mfma_f32_16x16x32_bf16 v[96:99], v[214:217], v[230:233], v[96:99]
	v_mfma_f32_16x16x32_bf16 v[84:87], v[206:209], v[238:241], v[84:87]
	v_mfma_f32_16x16x32_bf16 v[80:83], v[214:217], v[238:241], v[80:83]
	v_mfma_f32_16x16x32_bf16 v[68:71], v[206:209], v[246:249], v[68:71]
	v_mfma_f32_16x16x32_bf16 v[64:67], v[214:217], v[246:249], v[64:67]
	s_setprio 0
	s_barrier
	s_add_i32 s58, s58, s26
	v_lshl_add_u64 v[144:145], s[56:57], 0, v[134:135]
	s_mov_b32 m0, s58
	ds_read_b128 v[218:221], v149 offset:16384
	ds_read_b128 v[222:225], v149 offset:17408
	ds_read_b128 v[226:229], v149 offset:18432
	ds_read_b128 v[230:233], v149 offset:19456
	ds_read_b128 v[234:237], v149 offset:20480
	ds_read_b128 v[238:241], v149 offset:21504
	ds_read_b128 v[242:245], v149 offset:22528
	ds_read_b128 v[246:249], v149 offset:23552
	global_load_lds_dwordx4 v[144:145], off
	s_add_i32 m0, s58, 0x2000
	v_lshl_add_u64 v[154:155], s[56:57], 0, v[138:139]
	s_add_u32 s56, s56, s100
	s_addc_u32 s57, s57, 0
	s_add_i32 s55, s55, s26
	global_load_lds_dwordx4 v[154:155], off
	v_lshl_add_u64 v[170:171], s[56:57], 0, v[134:135]
	s_mov_b32 m0, s55
	v_lshl_add_u64 v[176:177], s[56:57], 0, v[138:139]
	global_load_lds_dwordx4 v[170:171], off
	s_add_i32 m0, s55, 0x2000
	v_lshl_add_u64 v[178:179], s[22:23], 0, v[132:133]
	global_load_lds_dwordx4 v[176:177], off
	s_mov_b32 m0, s27
	v_lshl_add_u64 v[180:181], s[22:23], 0, v[136:137]
	global_load_lds_dwordx4 v[178:179], off
	s_mov_b32 m0, s35
	s_nop 0
	global_load_lds_dwordx4 v[180:181], off
	s_waitcnt vmcnt(8)
	s_waitcnt lgkmcnt(0)
	s_barrier
	s_setprio 1
	s_waitcnt lgkmcnt(0)
	v_mfma_f32_16x16x32_bf16 v[60:63], v[150:153], v[218:221], v[60:63]
	v_mfma_f32_16x16x32_bf16 v[56:59], v[194:197], v[218:221], v[56:59]
	v_mfma_f32_16x16x32_bf16 v[44:47], v[150:153], v[226:229], v[44:47]
	v_mfma_f32_16x16x32_bf16 v[40:43], v[194:197], v[226:229], v[40:43]
	v_mfma_f32_16x16x32_bf16 v[28:31], v[150:153], v[234:237], v[28:31]
	v_mfma_f32_16x16x32_bf16 v[24:27], v[194:197], v[234:237], v[24:27]
	v_mfma_f32_16x16x32_bf16 v[12:15], v[150:153], v[242:245], v[12:15]
	v_mfma_f32_16x16x32_bf16 v[8:11], v[194:197], v[242:245], v[8:11]
	v_mfma_f32_16x16x32_bf16 v[60:63], v[190:193], v[222:225], v[60:63]
	v_mfma_f32_16x16x32_bf16 v[56:59], v[198:201], v[222:225], v[56:59]
	v_mfma_f32_16x16x32_bf16 v[44:47], v[190:193], v[230:233], v[44:47]
	v_mfma_f32_16x16x32_bf16 v[40:43], v[198:201], v[230:233], v[40:43]
	v_mfma_f32_16x16x32_bf16 v[28:31], v[190:193], v[238:241], v[28:31]
	v_mfma_f32_16x16x32_bf16 v[24:27], v[198:201], v[238:241], v[24:27]
	v_mfma_f32_16x16x32_bf16 v[12:15], v[190:193], v[246:249], v[12:15]
	v_mfma_f32_16x16x32_bf16 v[8:11], v[198:201], v[246:249], v[8:11]
	s_setprio 0
	s_setprio 1
	v_mfma_f32_16x16x32_bf16 v[52:55], v[202:205], v[218:221], v[52:55]
	v_mfma_f32_16x16x32_bf16 v[48:51], v[210:213], v[218:221], v[48:51]
	v_mfma_f32_16x16x32_bf16 v[36:39], v[202:205], v[226:229], v[36:39]
	v_mfma_f32_16x16x32_bf16 v[32:35], v[210:213], v[226:229], v[32:35]
	v_mfma_f32_16x16x32_bf16 v[20:23], v[202:205], v[234:237], v[20:23]
	v_mfma_f32_16x16x32_bf16 v[16:19], v[210:213], v[234:237], v[16:19]
	v_mfma_f32_16x16x32_bf16 v[4:7], v[202:205], v[242:245], v[4:7]
	v_mfma_f32_16x16x32_bf16 v[0:3], v[210:213], v[242:245], v[0:3]
	v_mfma_f32_16x16x32_bf16 v[52:55], v[206:209], v[222:225], v[52:55]
	v_mfma_f32_16x16x32_bf16 v[48:51], v[214:217], v[222:225], v[48:51]
	v_mfma_f32_16x16x32_bf16 v[36:39], v[206:209], v[230:233], v[36:39]
	v_mfma_f32_16x16x32_bf16 v[32:35], v[214:217], v[230:233], v[32:35]
	v_mfma_f32_16x16x32_bf16 v[20:23], v[206:209], v[238:241], v[20:23]
	v_mfma_f32_16x16x32_bf16 v[16:19], v[214:217], v[238:241], v[16:19]
	v_mfma_f32_16x16x32_bf16 v[4:7], v[206:209], v[246:249], v[4:7]
	v_mfma_f32_16x16x32_bf16 v[0:3], v[214:217], v[246:249], v[0:3]
	s_setprio 0
	s_barrier
	s_add_i32 s55, s8, 0x100
	v_add_u32_e32 v112, s55, v147
	s_add_i32 s56, s9, 0x100
	ds_read_b128 v[150:153], v112
	ds_read_b128 v[190:193], v112 offset:1024
	ds_read_b128 v[194:197], v112 offset:2048
	ds_read_b128 v[198:201], v112 offset:3072
	v_add_u32_e32 v112, s56, v147
	ds_read_b128 v[202:205], v112
	ds_read_b128 v[206:209], v112 offset:1024
	ds_read_b128 v[210:213], v112 offset:2048
	ds_read_b128 v[214:217], v112 offset:3072
	s_add_u32 s22, s22, s10
	s_addc_u32 s23, s23, 0
	s_mov_b32 m0, s40
	v_lshl_add_u64 v[118:119], s[22:23], 0, v[132:133]
	ds_read_b128 v[218:221], v149 offset:32768
	ds_read_b128 v[222:225], v149 offset:33792
	ds_read_b128 v[226:229], v149 offset:34816
	ds_read_b128 v[230:233], v149 offset:35840
	ds_read_b128 v[234:237], v149 offset:36864
	ds_read_b128 v[238:241], v149 offset:37888
	ds_read_b128 v[242:245], v149 offset:38912
	ds_read_b128 v[246:249], v149 offset:39936
	global_load_lds_dwordx4 v[118:119], off
	v_lshl_add_u64 v[118:119], s[22:23], 0, v[136:137]
	s_mov_b32 m0, s41
	s_nop 0
	global_load_lds_dwordx4 v[118:119], off
	s_waitcnt vmcnt(8)
	s_waitcnt lgkmcnt(0)
	s_barrier
	s_setprio 1
	s_waitcnt lgkmcnt(0)
	v_mfma_f32_16x16x32_bf16 v[128:131], v[150:153], v[218:221], v[128:131]
	v_mfma_f32_16x16x32_bf16 v[124:127], v[194:197], v[218:221], v[124:127]
	v_mfma_f32_16x16x32_bf16 v[108:111], v[150:153], v[226:229], v[108:111]
	v_mfma_f32_16x16x32_bf16 v[104:107], v[194:197], v[226:229], v[104:107]
	v_mfma_f32_16x16x32_bf16 v[92:95], v[150:153], v[234:237], v[92:95]
	v_mfma_f32_16x16x32_bf16 v[88:91], v[194:197], v[234:237], v[88:91]
	v_mfma_f32_16x16x32_bf16 v[76:79], v[150:153], v[242:245], v[76:79]
	v_mfma_f32_16x16x32_bf16 v[72:75], v[194:197], v[242:245], v[72:75]
	v_mfma_f32_16x16x32_bf16 v[128:131], v[190:193], v[222:225], v[128:131]
	v_mfma_f32_16x16x32_bf16 v[124:127], v[198:201], v[222:225], v[124:127]
	v_mfma_f32_16x16x32_bf16 v[108:111], v[190:193], v[230:233], v[108:111]
	v_mfma_f32_16x16x32_bf16 v[104:107], v[198:201], v[230:233], v[104:107]
	v_mfma_f32_16x16x32_bf16 v[92:95], v[190:193], v[238:241], v[92:95]
	v_mfma_f32_16x16x32_bf16 v[88:91], v[198:201], v[238:241], v[88:91]
	v_mfma_f32_16x16x32_bf16 v[76:79], v[190:193], v[246:249], v[76:79]
	v_mfma_f32_16x16x32_bf16 v[72:75], v[198:201], v[246:249], v[72:75]
	s_setprio 0
	s_setprio 1
	v_mfma_f32_16x16x32_bf16 v[118:121], v[202:205], v[218:221], v[120:123]
	v_mfma_f32_16x16x32_bf16 v[114:117], v[210:213], v[218:221], v[114:117]
	v_mfma_f32_16x16x32_bf16 v[100:103], v[202:205], v[226:229], v[100:103]
	v_mfma_f32_16x16x32_bf16 v[96:99], v[210:213], v[226:229], v[96:99]
	v_mfma_f32_16x16x32_bf16 v[84:87], v[202:205], v[234:237], v[84:87]
	v_mfma_f32_16x16x32_bf16 v[80:83], v[210:213], v[234:237], v[80:83]
	v_mfma_f32_16x16x32_bf16 v[68:71], v[202:205], v[242:245], v[68:71]
	v_mfma_f32_16x16x32_bf16 v[64:67], v[210:213], v[242:245], v[64:67]
	v_mfma_f32_16x16x32_bf16 v[120:123], v[206:209], v[222:225], v[118:121]
	v_mfma_f32_16x16x32_bf16 v[116:119], v[214:217], v[222:225], v[114:117]
	v_mfma_f32_16x16x32_bf16 v[100:103], v[206:209], v[230:233], v[100:103]
	v_mfma_f32_16x16x32_bf16 v[96:99], v[214:217], v[230:233], v[96:99]
	v_mfma_f32_16x16x32_bf16 v[84:87], v[206:209], v[238:241], v[84:87]
	v_mfma_f32_16x16x32_bf16 v[80:83], v[214:217], v[238:241], v[80:83]
	v_mfma_f32_16x16x32_bf16 v[68:71], v[206:209], v[246:249], v[68:71]
	v_mfma_f32_16x16x32_bf16 v[64:67], v[214:217], v[246:249], v[64:67]
	s_setprio 0
	s_barrier
	s_add_i32 s22, s55, s26
	v_lshl_add_u64 v[114:115], v[144:145], 0, s[30:31]
	s_mov_b32 m0, s22
	ds_read_b128 v[218:221], v149 offset:49152
	ds_read_b128 v[222:225], v149 offset:50176
	ds_read_b128 v[226:229], v149 offset:51200
	ds_read_b128 v[230:233], v149 offset:52224
	ds_read_b128 v[234:237], v149 offset:53248
	ds_read_b128 v[238:241], v149 offset:54272
	ds_read_b128 v[242:245], v149 offset:55296
	ds_read_b128 v[246:249], v149 offset:56320
	global_load_lds_dwordx4 v[114:115], off
	v_lshl_add_u64 v[114:115], v[154:155], 0, s[30:31]
	s_add_i32 m0, s22, 0x2000
	s_add_i32 s22, s56, s26
	global_load_lds_dwordx4 v[114:115], off
	v_lshl_add_u64 v[114:115], v[170:171], 0, s[30:31]
	s_mov_b32 m0, s22
	s_nop 0
	global_load_lds_dwordx4 v[114:115], off
	v_lshl_add_u64 v[114:115], v[176:177], 0, s[30:31]
	s_add_i32 m0, s22, 0x2000
	s_nop 0
	global_load_lds_dwordx4 v[114:115], off
	v_lshl_add_u64 v[114:115], v[178:179], 0, s[30:31]
	s_mov_b32 m0, s42
	s_nop 0
	global_load_lds_dwordx4 v[114:115], off
	v_lshl_add_u64 v[114:115], v[180:181], 0, s[30:31]
	s_mov_b32 m0, s43
	s_nop 0
	global_load_lds_dwordx4 v[114:115], off
	s_waitcnt vmcnt(8)
	s_waitcnt lgkmcnt(0)
	s_barrier
	s_setprio 1
	s_waitcnt lgkmcnt(0)
	v_mfma_f32_16x16x32_bf16 v[60:63], v[150:153], v[218:221], v[60:63]
	v_mfma_f32_16x16x32_bf16 v[56:59], v[194:197], v[218:221], v[56:59]
	v_mfma_f32_16x16x32_bf16 v[44:47], v[150:153], v[226:229], v[44:47]
	v_mfma_f32_16x16x32_bf16 v[40:43], v[194:197], v[226:229], v[40:43]
	v_mfma_f32_16x16x32_bf16 v[28:31], v[150:153], v[234:237], v[28:31]
	v_mfma_f32_16x16x32_bf16 v[24:27], v[194:197], v[234:237], v[24:27]
	v_mfma_f32_16x16x32_bf16 v[12:15], v[150:153], v[242:245], v[12:15]
	v_mfma_f32_16x16x32_bf16 v[8:11], v[194:197], v[242:245], v[8:11]
	v_mfma_f32_16x16x32_bf16 v[60:63], v[190:193], v[222:225], v[60:63]
	v_mfma_f32_16x16x32_bf16 v[56:59], v[198:201], v[222:225], v[56:59]
	v_mfma_f32_16x16x32_bf16 v[44:47], v[190:193], v[230:233], v[44:47]
	v_mfma_f32_16x16x32_bf16 v[40:43], v[198:201], v[230:233], v[40:43]
	v_mfma_f32_16x16x32_bf16 v[28:31], v[190:193], v[238:241], v[28:31]
	v_mfma_f32_16x16x32_bf16 v[24:27], v[198:201], v[238:241], v[24:27]
	v_mfma_f32_16x16x32_bf16 v[12:15], v[190:193], v[246:249], v[12:15]
	v_mfma_f32_16x16x32_bf16 v[8:11], v[198:201], v[246:249], v[8:11]
	s_setprio 0
	s_setprio 1
	v_mfma_f32_16x16x32_bf16 v[52:55], v[202:205], v[218:221], v[52:55]
	v_mfma_f32_16x16x32_bf16 v[48:51], v[210:213], v[218:221], v[48:51]
	v_mfma_f32_16x16x32_bf16 v[36:39], v[202:205], v[226:229], v[36:39]
	v_mfma_f32_16x16x32_bf16 v[32:35], v[210:213], v[226:229], v[32:35]
	v_mfma_f32_16x16x32_bf16 v[20:23], v[202:205], v[234:237], v[20:23]
	v_mfma_f32_16x16x32_bf16 v[16:19], v[210:213], v[234:237], v[16:19]
	v_mfma_f32_16x16x32_bf16 v[4:7], v[202:205], v[242:245], v[4:7]
	v_mfma_f32_16x16x32_bf16 v[0:3], v[210:213], v[242:245], v[0:3]
	v_mfma_f32_16x16x32_bf16 v[52:55], v[206:209], v[222:225], v[52:55]
	v_mfma_f32_16x16x32_bf16 v[48:51], v[214:217], v[222:225], v[48:51]
	v_mfma_f32_16x16x32_bf16 v[36:39], v[206:209], v[230:233], v[36:39]
	v_mfma_f32_16x16x32_bf16 v[32:35], v[214:217], v[230:233], v[32:35]
	v_mfma_f32_16x16x32_bf16 v[20:23], v[206:209], v[238:241], v[20:23]
	v_mfma_f32_16x16x32_bf16 v[16:19], v[214:217], v[238:241], v[16:19]
	v_mfma_f32_16x16x32_bf16 v[4:7], v[206:209], v[246:249], v[4:7]
	v_mfma_f32_16x16x32_bf16 v[0:3], v[214:217], v[246:249], v[0:3]
	s_setprio 0
	s_add_u32 s20, s20, 0x100
	s_addc_u32 s21, s21, 0
	s_add_u32 s38, s38, 0x100
	s_addc_u32 s39, s39, 0
	s_cmp_ge_u32 s54, s34
	s_cselect_b32 s101, 1, 0
	s_mov_b32 s22, s54
	s_add_i32 s54, s22, 2
	s_add_u32 s55, s20, 0x80
	s_addc_u32 s23, s21, 0
	s_add_i32 s58, s33, 0x100
	s_cmp_eq_u32 s44, s22
	s_cselect_b32 s23, s1, s23
	s_cselect_b32 s22, s0, s55
	v_add_u32_e32 v112, s58, v147
	s_cselect_b32 s57, s19, s39
	s_cselect_b32 s56, s18, s38
	s_add_i32 s55, s29, 0x100
	s_barrier
	s_cmp_eq_u32 s101, 0
	s_cbranch_scc1 .LBB0_675
